# v62 + attention: next unit's Q fragment prefetched into registers at the start of the current unit's tail
# speedup vs baseline: 1.0076x; 1.0076x over previous
.LBB0_546:
	s_and_b32 s77, s76, 1
	s_lshl_b32 s0, s77, 2
	s_add_i32 s8, s0, 0
	s_add_i32 s0, s8, 0x26820
	v_mov_b32_e32 v0, s0
	ds_read_b32 v0, v0
	s_mov_b64 s[0:1], -1
	s_waitcnt lgkmcnt(0)
	v_readfirstlane_b32 s9, v0
	s_cmpk_gt_i32 s9, 0x3ff
	s_cbranch_scc1 .LBB0_545
	s_ashr_i32 s0, s9, 6
	s_lshl_b32 s0, s0, 2
	s_add_i32 s0, s0, 0
	s_add_i32 s0, s0, 0x26840
	v_mov_b32_e32 v0, s0
	ds_read_b32 v0, v0
	v_mov_b32_e32 v48, v196
	s_add_i32 s1, s8, 0x26800
	s_waitcnt lgkmcnt(0)
	v_readfirstlane_b32 s0, v0
	v_readfirstlane_b32 s15, v48
	v_mov_b32_e32 v0, s1
	s_not_b32 s1, s9
	s_ashr_i32 s78, s15, 6
	s_lshl_b32 s1, s1, 8
	s_and_b32 s79, s1, 0x3f00
	s_lshl_b32 s82, s78, 5
	s_add_i32 s8, s82, s79
	s_ashr_i32 s9, s8, 31
	ds_read_b32 v0, v0
	s_lshl_b64 s[8:9], s[8:9], 11
	s_add_u32 s1, s42, s8
	s_addc_u32 s11, s43, s9
	s_lshl_b32 s8, s0, 6
	s_ashr_i32 s9, s8, 31
	s_lshl_b64 s[12:13], s[8:9], 1
	s_waitcnt lgkmcnt(0)
	v_readfirstlane_b32 s10, v0
	s_add_u32 s8, s1, s12
	s_addc_u32 s9, s11, s13
	s_ashr_i32 s11, s10, 31
	s_lshl_b64 s[16:17], s[10:11], 17
	s_add_u32 s1, s44, s16
	s_addc_u32 s11, s45, s17
	s_add_u32 s56, s1, s12
	s_addc_u32 s57, s11, s13
	s_add_u32 s1, s46, s16
	v_and_b32_e32 v206, 63, v48
	s_addc_u32 s11, s47, s17
	s_add_u32 s16, s1, s12
	v_lshlrev_b32_e32 v0, 11, v206
	s_addc_u32 s17, s11, s13
	v_lshl_add_u64 v[2:3], s[56:57], 0, v[0:1]
	s_lshl_b32 s1, s78, 4
	v_bfe_u32 v0, v48, 2, 4
	s_lshl_b32 s56, s78, 3
	v_and_or_b32 v0, s1, 48, v0
	s_ashr_i32 s57, s56, 31
	v_lshlrev_b32_e32 v0, 11, v0
	s_ashr_i32 s1, s15, 3
	v_lshl_add_u64 v[198:199], s[56:57], 1, v[2:3]
	v_lshl_add_u64 v[2:3], s[16:17], 0, v[0:1]
	s_and_b32 s16, s1, 0xffffffe0
	s_ashr_i32 s17, s16, 31
	s_lshl_b32 s14, s78, 10
	v_lshlrev_b32_e32 v0, 3, v48
	s_cmp_lg_u32 0, -1
	v_and_b32_e32 v209, 24, v0
	s_cselect_b32 s1, 0, 0
	v_and_b32_e32 v207, 31, v48
	v_lshl_add_u64 v[2:3], s[16:17], 1, v[2:3]
	v_lshlrev_b32_e32 v0, 1, v209
	s_add_i32 s83, s14, s1
	s_mov_b32 s1, m0
	s_mov_b32 m0, s83
	s_nop 0
	global_load_lds_dwordx4 v[198:199], off
	s_mov_b32 m0, s1
	v_bfe_u32 v208, v48, 5, 1
	v_lshl_add_u64 v[200:201], v[2:3], 0, v[0:1]
	s_add_i32 s84, s83, 0x6000
	v_lshlrev_b32_e32 v0, 11, v207
	v_lshl_or_b32 v0, v208, 4, v0
	s_cmp_lg_u32 s76, 0
	s_cbranch_scc1 .Lmy_qpf_hskip
	global_load_dwordx4 v[124:127], v0, s[8:9]
	global_load_dwordx4 v[120:123], v0, s[8:9] offset:32
	global_load_dwordx4 v[116:119], v0, s[8:9] offset:64
	global_load_dwordx4 v[112:115], v0, s[8:9] offset:96
.Lmy_qpf_hskip:
	s_add_i32 s11, s79, 0x100
	s_lshl_b32 s16, s10, 6
	s_sub_i32 s20, s11, s16
	v_cmp_gt_i32_e32 vcc, s20, v48
	s_and_saveexec_b64 s[60:61], vcc
	s_cbranch_execz .LBB0_556
	s_lshl_b32 s1, s77, 10
	s_add_i32 s56, s1, 0
	s_ashr_i32 s1, s0, 31
	s_add_i32 s56, s56, 0x24800
	s_lshl_b64 s[0:1], s[0:1], 16
	s_add_u32 s33, s38, s0
	s_addc_u32 s57, s39, s1
	s_ashr_i32 s17, s16, 31
	s_lshl_b64 s[8:9], s[16:17], 2
	s_add_u32 s62, s33, s8
	s_addc_u32 s63, s57, s9
	s_add_u32 s8, s38, s8
	s_addc_u32 s9, s39, s9
	s_add_u32 s0, s8, s0
	v_ashrrev_i32_e32 v49, 31, v48
	s_addc_u32 s1, s9, s1
	v_lshl_add_u32 v0, v48, 2, s69
	v_lshl_add_u64 v[2:3], v[48:49], 2, s[0:1]
	s_mov_b64 s[64:65], 0
	v_mov_b32_e32 v4, v48
	s_branch .LBB0_550

.LBB0_562:
	v_max3_f32 v32, v0, v23, v30
	v_max3_f32 v34, v2, v3, v33
	s_and_b32 s0, s15, 0x3fffffc0
	v_max3_f32 v32, v32, v28, v31
	v_max3_f32 v34, v34, v6, v7
	s_lshl_b32 s0, s0, 2
	v_max3_f32 v32, v32, v4, v5
	v_max3_f32 v34, v34, v24, v27
	s_add_i32 s85, s0, 0
	v_max3_f32 v32, v32, v26, v29
	v_max3_f32 v34, v34, v10, v11
	s_add_i32 s0, 0, 0x14800
	v_max3_f32 v32, v32, v8, v9
	v_max3_f32 v34, v34, v20, v21
	s_cmp_lg_u32 0, -1
	v_max3_f32 v32, v32, v22, v25
	v_max3_f32 v34, v34, v14, v15
	s_mov_b32 s15, 1
	v_max3_f32 v32, v32, v12, v13
	v_max3_f32 v34, v34, v16, v17
	s_mov_b32 s20, 0
	v_max3_f32 v32, v32, v18, v19
	v_lshl_add_u32 v214, v207, 2, s85
	v_max_f32_e32 v32, v32, v34
	s_nop 0
	v_mov_b32_e32 v34, v32
	s_nop 1
	v_permlane32_swap_b32_e32 v32, v34
	v_max_f32_e32 v32, v32, v34
	v_lshlrev_b32_e32 v34, 1, v48
	v_sub_f32_e32 v0, v0, v32
	v_sub_f32_e32 v30, v30, v32
	v_sub_f32_e32 v23, v23, v32
	v_sub_f32_e32 v33, v33, v32
	v_sub_f32_e32 v2, v2, v32
	v_sub_f32_e32 v28, v28, v32
	v_sub_f32_e32 v3, v3, v32
	v_sub_f32_e32 v31, v31, v32
	v_sub_f32_e32 v4, v4, v32
	v_sub_f32_e32 v26, v26, v32
	v_sub_f32_e32 v5, v5, v32
	v_sub_f32_e32 v29, v29, v32
	v_sub_f32_e32 v6, v6, v32
	v_sub_f32_e32 v24, v24, v32
	v_sub_f32_e32 v7, v7, v32
	v_sub_f32_e32 v27, v27, v32
	v_sub_f32_e32 v8, v8, v32
	v_sub_f32_e32 v22, v22, v32
	v_sub_f32_e32 v9, v9, v32
	v_sub_f32_e32 v25, v25, v32
	v_sub_f32_e32 v10, v10, v32
	v_sub_f32_e32 v20, v20, v32
	v_sub_f32_e32 v11, v11, v32
	v_sub_f32_e32 v21, v21, v32
	v_sub_f32_e32 v12, v12, v32
	v_sub_f32_e32 v18, v18, v32
	v_sub_f32_e32 v13, v13, v32
	v_sub_f32_e32 v19, v19, v32
	v_sub_f32_e32 v14, v14, v32
	v_sub_f32_e32 v16, v16, v32
	v_sub_f32_e32 v15, v15, v32
	v_sub_f32_e32 v17, v17, v32
	s_nop 0
	v_exp_f32_e32 v96, v0
	v_add_u32_e32 v0, s0, v217
	v_sub_f32_e64 v219, -v1, v32
	v_exp_f32_e32 v97, v23
	v_exp_f32_e32 v98, v2
	v_exp_f32_e32 v99, v3
	v_exp_f32_e32 v100, v4
	v_exp_f32_e32 v101, v5
	v_exp_f32_e32 v102, v6
	v_exp_f32_e32 v103, v7
	v_exp_f32_e32 v104, v8
	v_exp_f32_e32 v105, v9
	v_exp_f32_e32 v106, v10
	v_exp_f32_e32 v107, v11
	v_exp_f32_e32 v108, v12
	v_exp_f32_e32 v109, v13
	v_exp_f32_e32 v110, v14
	v_exp_f32_e32 v111, v15
	v_exp_f32_e32 v80, v30
	v_exp_f32_e32 v81, v33
	v_exp_f32_e32 v82, v28
	v_exp_f32_e32 v83, v31
	v_exp_f32_e32 v84, v26
	v_exp_f32_e32 v85, v29
	v_exp_f32_e32 v86, v24
	v_exp_f32_e32 v87, v27
	v_exp_f32_e32 v88, v22
	v_exp_f32_e32 v89, v25
	v_exp_f32_e32 v90, v20
	v_exp_f32_e32 v91, v21
	v_exp_f32_e32 v92, v18
	v_exp_f32_e32 v93, v19
	v_exp_f32_e32 v94, v16
	v_exp_f32_e32 v95, v17
	ds_read_b128 v[2:5], v0 offset:256
	ds_read_b128 v[6:9], v0 offset:288
	ds_read_b128 v[10:13], v0 offset:320
	ds_read_b128 v[14:17], v0 offset:352
	ds_read_b128 v[18:21], v0 offset:384
	ds_read_b128 v[22:25], v0 offset:416
	ds_read_b128 v[26:29], v0 offset:448
	ds_read_b128 v[30:33], v0 offset:480
	s_waitcnt vmcnt(0) lgkmcnt(0)
	s_barrier
	v_readfirstlane_b32 s60, v196
	s_cmp_lt_u32 s60, 64
	s_cbranch_scc0 .Lmy_qpf_nopub
	v_readfirstlane_b32 s60, v210
	v_mov_b32_e32 v35, 0x27f00
	v_mov_b32_e32 v36, s60
	ds_write_b32 v35, v36
.Lmy_qpf_nopub:
	s_waitcnt lgkmcnt(7)
	v_sub_f32_e32 v65, v219, v3
	v_sub_f32_e32 v64, v219, v2
	v_lshl_add_u64 v[2:3], v[198:199], 0, s[40:41]
	s_mov_b32 s0, m0
	s_mov_b32 m0, s83
	s_nop 0
	global_load_lds_dwordx4 v[2:3], off
	s_mov_b32 m0, s0
	s_cselect_b32 s0, 0, 0
	s_add_i32 s0, s0, s14
	v_lshl_add_u64 v[2:3], v[200:201], 0, s[22:23]
	s_add_i32 s0, s0, 0x8000
	s_mov_b32 s1, m0
	s_mov_b32 m0, s0
	s_nop 0
	global_load_lds_dwordx4 v[2:3], off
	s_mov_b32 m0, s1
	ds_read_b128 v[172:175], v216 offset:8192
	ds_read_b128 v[168:171], v216 offset:8704
	ds_read_b128 v[164:167], v216 offset:10240
	ds_read_b128 v[160:163], v216 offset:10752
	ds_read_b128 v[156:159], v216 offset:12288
	ds_read_b128 v[152:155], v216 offset:12800
	ds_read_b128 v[148:151], v216 offset:14336
	ds_read_b128 v[144:147], v216 offset:14848
	v_and_b32_e32 v213, 32, v34
	v_lshlrev_b32_e32 v34, 4, v48
	v_and_b32_e32 v34, 0xc0, v34
	s_waitcnt vmcnt(2) lgkmcnt(0)
	s_barrier
	v_lshl_or_b32 v212, v208, 8, v34
	v_add_u32_e32 v34, 0, v213
	v_add3_u32 v218, v34, v209, v212
	s_waitcnt lgkmcnt(12)
	v_sub_f32_e32 v79, v219, v17
	v_sub_f32_e32 v78, v219, v16
	v_sub_f32_e32 v77, v219, v15
	v_sub_f32_e32 v76, v219, v14
	v_sub_f32_e32 v75, v219, v13
	v_sub_f32_e32 v74, v219, v12
	v_sub_f32_e32 v73, v219, v11
	v_sub_f32_e32 v72, v219, v10
	v_sub_f32_e32 v71, v219, v9
	v_sub_f32_e32 v70, v219, v8
	v_sub_f32_e32 v69, v219, v7
	v_sub_f32_e32 v68, v219, v6
	v_sub_f32_e32 v67, v219, v5
	v_sub_f32_e32 v66, v219, v4
	s_waitcnt lgkmcnt(8)
	v_sub_f32_e32 v63, v219, v33
	v_sub_f32_e32 v62, v219, v32
	v_sub_f32_e32 v61, v219, v31
	v_sub_f32_e32 v60, v219, v30
	v_sub_f32_e32 v59, v219, v29
	v_sub_f32_e32 v58, v219, v28
	v_sub_f32_e32 v57, v219, v27
	v_sub_f32_e32 v56, v219, v26
	v_sub_f32_e32 v55, v219, v25
	v_sub_f32_e32 v54, v219, v24
	v_sub_f32_e32 v53, v219, v23
	v_sub_f32_e32 v52, v219, v22
	v_sub_f32_e32 v51, v219, v21
	v_sub_f32_e32 v50, v219, v20
	v_sub_f32_e32 v49, v219, v19
	v_sub_f32_e32 v48, v219, v18
	s_cmp_lt_i32 s86, 7
	v_cmp_gt_u32_e64 s[0:1], 32, v206
	s_cbranch_scc1 .LBB0_578
	v_mov_b32_e32 v14, v1
	v_mov_b32_e32 v15, v1
	v_mov_b32_e32 v0, v1
	v_mov_b32_e32 v2, v1
	v_mov_b32_e32 v3, v1
	v_mov_b32_e32 v4, v1
	v_mov_b32_e32 v5, v1
	v_mov_b32_e32 v6, v1
	v_mov_b32_e32 v7, v1
	v_mov_b32_e32 v8, v1
	v_mov_b32_e32 v9, v1
	v_mov_b32_e32 v10, v1
	v_mov_b32_e32 v11, v1
	v_mov_b32_e32 v12, v1
	v_mov_b32_e32 v13, v1
	v_mov_b64_e32 v[46:47], v[14:15]
	v_mov_b64_e32 v[30:31], v[14:15]
	v_add_u32_e32 v188, s71, v217
	v_lshl_add_u64 v[184:185], v[200:201], 0, s[40:41]
	v_lshl_add_u64 v[186:187], v[198:199], 0, s[50:51]
	s_mov_b32 s15, 0
	s_movk_i32 s20, 0x4000
	s_movk_i32 s14, 0x2000
	v_mov_b32_e32 v220, 0
	s_mov_b32 s57, 6
	v_mov_b64_e32 v[44:45], v[12:13]
	v_mov_b64_e32 v[42:43], v[10:11]
	v_mov_b64_e32 v[40:41], v[8:9]
	v_mov_b64_e32 v[38:39], v[6:7]
	v_mov_b64_e32 v[36:37], v[4:5]
	v_mov_b64_e32 v[34:35], v[2:3]
	v_mov_b64_e32 v[32:33], v[0:1]
	v_mov_b64_e32 v[28:29], v[12:13]
	v_mov_b64_e32 v[26:27], v[10:11]
	v_mov_b64_e32 v[24:25], v[8:9]
	v_mov_b64_e32 v[22:23], v[6:7]
	v_mov_b64_e32 v[20:21], v[4:5]
	v_mov_b64_e32 v[18:19], v[2:3]
	v_mov_b64_e32 v[16:17], v[0:1]

.LBB0_650:
	v_mov_b32_e32 v100, 0x27f00
	ds_read_b32 v100, v100
	s_waitcnt lgkmcnt(0)
	v_readfirstlane_b32 s60, v100
	s_min_u32 s60, s60, 0x3ff
	s_lshr_b32 s61, s60, 6
	s_lshl_b32 s61, s61, 2
	s_add_i32 s61, s61, 0x26840
	v_mov_b32_e32 v100, s61
	ds_read_b32 v100, v100
	s_not_b32 s62, s60
	s_lshl_b32 s62, s62, 8
	s_and_b32 s62, s62, 0x3f00
	v_readfirstlane_b32 s63, v196
	s_lshr_b32 s63, s63, 6
	s_lshl_b32 s63, s63, 5
	s_add_i32 s62, s62, s63
	s_mov_b32 s63, 0
	s_lshl_b64 s[62:63], s[62:63], 11
	s_add_u32 s62, s42, s62
	s_addc_u32 s63, s43, s63
	v_lshlrev_b32_e32 v101, 11, v207
	v_lshl_or_b32 v101, v208, 4, v101
	s_waitcnt lgkmcnt(0)
	v_readfirstlane_b32 s61, v100
	s_lshl_b32 s61, s61, 7
	s_add_u32 s62, s62, s61
	s_addc_u32 s63, s63, 0
	global_load_dwordx4 v[124:127], v101, s[62:63]
	global_load_dwordx4 v[120:123], v101, s[62:63] offset:32
	global_load_dwordx4 v[116:119], v101, s[62:63] offset:64
	global_load_dwordx4 v[112:115], v101, s[62:63] offset:96
	v_add_f32_e32 v0, v64, v65
	v_add_f32_e32 v0, v66, v0
	v_add_f32_e32 v0, v67, v0
	v_add_f32_e32 v0, v68, v0
	v_add_f32_e32 v0, v69, v0
	v_add_f32_e32 v0, v70, v0
	v_add_f32_e32 v0, v71, v0
	v_add_f32_e32 v0, v72, v0
	v_add_f32_e32 v0, v73, v0
	v_add_f32_e32 v0, v74, v0
	v_add_f32_e32 v0, v75, v0
	v_add_f32_e32 v0, v76, v0
	v_add_f32_e32 v0, v77, v0
	v_add_f32_e32 v0, v78, v0
	v_add_f32_e32 v0, v79, v0
	v_add_f32_e32 v0, v48, v0
	v_add_f32_e32 v0, v49, v0
	v_add_f32_e32 v0, v50, v0
	v_add_f32_e32 v0, v51, v0
	v_add_f32_e32 v0, v52, v0
	v_add_f32_e32 v0, v53, v0
	v_add_f32_e32 v0, v54, v0
	v_add_f32_e32 v0, v55, v0
	v_add_f32_e32 v0, v56, v0
	v_add_f32_e32 v0, v57, v0
	v_add_f32_e32 v0, v58, v0
	v_add_f32_e32 v0, v59, v0
	v_add_f32_e32 v0, v60, v0
	s_lshl_b64 s[16:17], s[10:11], 10
	v_add_f32_e32 v0, v61, v0
	s_cmp_lg_u32 0, -1
	v_add_f32_e32 v0, v62, v0
	s_cselect_b32 s10, 0, 0
	v_add_f32_e32 v0, v63, v0
	s_addk_i32 s10, 0x6000
	v_add_f32_e32 v0, v93, v0
	v_cvt_pk_bf16_f32 v48, v48, v49
	v_add3_u32 v95, v213, s10, v209
	v_cvt_pk_bf16_f32 v64, v64, v65
	v_cvt_pk_bf16_f32 v65, v66, v67
	v_cvt_pk_bf16_f32 v66, v68, v69
	v_cvt_pk_bf16_f32 v67, v70, v71
	v_cvt_pk_bf16_f32 v68, v72, v73
	v_cvt_pk_bf16_f32 v69, v74, v75
	v_cvt_pk_bf16_f32 v70, v76, v77
	v_cvt_pk_bf16_f32 v71, v78, v79
	v_cvt_pk_bf16_f32 v49, v50, v51
	v_cvt_pk_bf16_f32 v50, v52, v53
	v_cvt_pk_bf16_f32 v51, v54, v55
	v_cvt_pk_bf16_f32 v52, v56, v57
	v_cvt_pk_bf16_f32 v53, v58, v59
	v_cvt_pk_bf16_f32 v54, v60, v61
	v_cvt_pk_bf16_f32 v55, v62, v63
	v_add3_u32 v93, v95, v212, s87
	ds_read_b64_tr_b16 v[56:57],v93 offset:0
	ds_read_b64_tr_b16 v[58:59],v93 offset:512
	ds_read_b64_tr_b16 v[60:61],v93 offset:1024
	ds_read_b64_tr_b16 v[62:63],v93 offset:1536
	ds_read_b64_tr_b16 v[72:73],v93 offset:2048
	ds_read_b64_tr_b16 v[74:75],v93 offset:2560
	ds_read_b64_tr_b16 v[76:77],v93 offset:3072
	ds_read_b64_tr_b16 v[78:79],v93 offset:3584
	s_waitcnt lgkmcnt(0)
	s_nop 0
	v_mfma_f32_32x32x16_bf16 v[32:47], v[64:67], v[56:59], v[32:47]
	ds_read_b64_tr_b16 v[56:57],v93 offset:4096
	ds_read_b64_tr_b16 v[58:59],v93 offset:4608
	v_mfma_f32_32x32x16_bf16 v[32:47], v[68:71], v[60:63], v[32:47]
	ds_read_b64_tr_b16 v[60:61],v93 offset:5120
	ds_read_b64_tr_b16 v[62:63],v93 offset:5632
	v_mfma_f32_32x32x16_bf16 v[32:47], v[48:51], v[72:75], v[32:47]
	ds_read_b64_tr_b16 v[72:73],v93 offset:6144
	ds_read_b64_tr_b16 v[74:75],v93 offset:6656
	ds_read_b64_tr_b16 v[96:97],v93 offset:7168
	ds_read_b64_tr_b16 v[98:99],v93 offset:7680
	s_waitcnt lgkmcnt(0)
	v_mfma_f32_32x32x16_bf16 v[32:47], v[52:55], v[76:79], v[32:47]
	v_mfma_f32_32x32x16_bf16 v[16:31], v[64:67], v[56:59], v[16:31]
	v_cmp_gt_u32_e64 s[10:11], 32, v206
	v_mfma_f32_32x32x16_bf16 v[16:31], v[68:71], v[60:63], v[16:31]
	v_mfma_f32_32x32x16_bf16 v[16:31], v[48:51], v[72:75], v[16:31]
	v_mov_b32_e32 v48, v0
	s_nop 1
	v_permlane32_swap_b32_e32 v0, v48
	v_mfma_f32_32x32x16_bf16 v[16:31], v[52:55], v[96:99], v[16:31]
	s_and_saveexec_b64 s[60:61], s[10:11]
	v_add_f32_e32 v0, v0, v48
	ds_write_b32 v214, v0 offset:49280
	s_or_b64 exec, exec, s[60:61]
	s_waitcnt lgkmcnt(0)
	ds_read_b128 v[48:51], v94 offset:49280
	ds_read_b128 v[52:55], v94 offset:49312
	s_lshl_b64 s[16:17], s[16:17], 1
	s_add_u32 s16, s28, s16
	s_addc_u32 s17, s29, s17
	s_waitcnt lgkmcnt(1)
	v_rcp_f32_e32 v0, v48
	v_rcp_f32_e32 v56, v49
	s_add_u32 s12, s16, s12
	s_addc_u32 s13, s17, s13
	s_lshl_b32 s16, s78, 12
	s_add_i32 s16, s16, 0
	v_lshlrev_b32_e32 v63, 1, v207
	v_lshlrev_b32_e32 v64, 9, v208
	v_mul_f32_e32 v32, v32, v0
	v_mul_f32_e32 v0, v16, v0
	v_add3_u32 v63, s16, v63, v64
	v_cvt_pk_bf16_f32 v0, v0, s0
	v_rcp_f32_e32 v57, v50
	v_rcp_f32_e32 v58, v51
	s_waitcnt lgkmcnt(0)
	v_rcp_f32_e32 v59, v52
	ds_read_b128 v[48:51], v94 offset:49344
	v_rcp_f32_e32 v60, v53
	v_rcp_f32_e32 v61, v54
	v_rcp_f32_e32 v62, v55
	ds_read_b128 v[52:55], v94 offset:49376
	ds_write_b16 v63, v0 offset:51264
	v_mul_f32_e32 v0, v33, v56
	v_cvt_pk_bf16_f32 v0, v0, s0
	ds_write_b16 v63, v0 offset:51328
	v_mul_f32_e32 v0, v17, v56
	v_cvt_pk_bf16_f32 v0, v0, s0
	ds_write_b16 v63, v0 offset:51392
	v_mul_f32_e32 v0, v34, v57
	v_cvt_pk_bf16_f32 v0, v0, s0
	ds_write_b16 v63, v0 offset:51456
	v_mul_f32_e32 v0, v18, v57
	v_cvt_pk_bf16_f32 v0, v0, s0
	ds_write_b16 v63, v0 offset:51520
	v_mul_f32_e32 v0, v35, v58
	v_cvt_pk_bf16_f32 v0, v0, s0
	ds_write_b16 v63, v0 offset:51584
	v_mul_f32_e32 v0, v19, v58
	v_cvt_pk_bf16_f32 v0, v0, s0
	ds_write_b16 v63, v0 offset:51648
	v_mul_f32_e32 v0, v36, v59
	v_cvt_pk_bf16_f32 v0, v0, s0
	ds_write_b16 v63, v0 offset:52224
	v_mul_f32_e32 v0, v20, v59
	v_cvt_pk_bf16_f32 v0, v0, s0
	ds_write_b16 v63, v0 offset:52288
	v_mul_f32_e32 v0, v37, v60
	v_cvt_pk_bf16_f32 v0, v0, s0
	ds_write_b16 v63, v0 offset:52352
	v_mul_f32_e32 v0, v21, v60
	v_cvt_pk_bf16_f32 v0, v0, s0
	ds_write_b16 v63, v0 offset:52416
	v_mul_f32_e32 v0, v38, v61
	v_cvt_pk_bf16_f32 v0, v0, s0
	ds_write_b16 v63, v0 offset:52480
	v_mul_f32_e32 v0, v22, v61
	v_cvt_pk_bf16_f32 v0, v0, s0
	s_waitcnt lgkmcnt(13)
	v_rcp_f32_e32 v48, v48
	ds_write_b16 v63, v0 offset:52544
	v_mul_f32_e32 v0, v39, v62
	v_cvt_pk_bf16_f32 v0, v0, s0
	ds_write_b16 v63, v0 offset:52608
	v_mul_f32_e32 v0, v23, v62
	v_cvt_pk_bf16_f32 v0, v0, s0
	v_rcp_f32_e32 v49, v49
	ds_write_b16 v63, v0 offset:52672
	v_mul_f32_e32 v0, v40, v48
	v_cvt_pk_bf16_f32 v0, v0, s0
	ds_write_b16 v63, v0 offset:53248
	v_mul_f32_e32 v0, v24, v48
	v_cvt_pk_bf16_f32 v0, v0, s0
	v_rcp_f32_e32 v50, v50
	ds_write_b16 v63, v0 offset:53312
	v_mul_f32_e32 v0, v41, v49
	v_cvt_pk_bf16_f32 v0, v0, s0
	ds_write_b16 v63, v0 offset:53376
	v_mul_f32_e32 v0, v25, v49
	v_cvt_pk_bf16_f32 v0, v0, s0
	v_rcp_f32_e32 v51, v51
	ds_write_b16 v63, v0 offset:53440
	v_mul_f32_e32 v0, v42, v50
	v_cvt_pk_bf16_f32 v0, v0, s0
	ds_write_b16 v63, v0 offset:53504
	v_mul_f32_e32 v0, v26, v50
	v_cvt_pk_bf16_f32 v0, v0, s0
	s_waitcnt lgkmcnt(14)
	v_rcp_f32_e32 v52, v52
	ds_write_b16 v63, v0 offset:53568
	v_mul_f32_e32 v0, v43, v51
	v_cvt_pk_bf16_f32 v0, v0, s0
	ds_write_b16 v63, v0 offset:53632
	v_mul_f32_e32 v0, v27, v51
	v_cvt_pk_bf16_f32 v0, v0, s0
	v_rcp_f32_e32 v53, v53
	ds_write_b16 v63, v0 offset:53696
	v_mul_f32_e32 v0, v44, v52
	v_cvt_pk_bf16_f32 v0, v0, s0
	ds_write_b16 v63, v0 offset:54272
	v_mul_f32_e32 v0, v28, v52
	v_cvt_pk_bf16_f32 v0, v0, s0
	v_rcp_f32_e32 v54, v54
	ds_write_b16 v63, v0 offset:54336
	v_mul_f32_e32 v0, v45, v53
	v_cvt_pk_bf16_f32 v0, v0, s0
	ds_write_b16 v63, v0 offset:54400
	v_mul_f32_e32 v0, v29, v53
	v_cvt_pk_bf16_f32 v0, v0, s0
	v_rcp_f32_e32 v55, v55
	ds_write_b16 v63, v0 offset:54464
	v_mul_f32_e32 v0, v46, v54
	v_cvt_pk_bf16_f32 v0, v0, s0
	ds_write_b16 v63, v0 offset:54528
	v_mul_f32_e32 v0, v30, v54
	v_cvt_pk_bf16_f32 v0, v0, s0
	ds_write_b16 v63, v0 offset:54592
	v_mul_f32_e32 v0, v47, v55
	v_cvt_pk_bf16_f32 v0, v0, s0
	ds_write_b16 v63, v0 offset:54656
	v_mul_f32_e32 v0, v31, v55
	v_cvt_pk_bf16_f32 v32, v32, s0
	v_cvt_pk_bf16_f32 v0, v0, s0
	ds_write_b16 v63, v32 offset:51200
	ds_write_b16 v63, v0 offset:54720
	v_lshlrev_b32_e32 v0, 7, v14
	v_lshlrev_b32_e32 v14, 1, v90
	s_waitcnt lgkmcnt(0)
	v_add3_u32 v0, s16, v0, v14
	ds_read_b128 v[16:19], v0 offset:51200
	ds_read_b128 v[20:23], v0 offset:52224
	s_waitcnt vmcnt(7)
	v_lshlrev_b32_e32 v28, 16, v80
	v_and_b32_e32 v29, 0xffff0000, v80
	v_lshl_add_u64 v[24:25], v[88:89], 1, s[12:13]
	s_waitcnt lgkmcnt(1)
	v_lshlrev_b32_e32 v26, 16, v16
	v_and_b32_e32 v27, 0xffff0000, v16
	v_pk_mul_f32 v[26:27], v[28:29], v[26:27]
	v_lshlrev_b32_e32 v28, 16, v81
	v_cvt_pk_bf16_f32 v16, v26, v27
	v_lshlrev_b32_e32 v26, 16, v17
	v_and_b32_e32 v27, 0xffff0000, v17
	v_and_b32_e32 v29, 0xffff0000, v81
	v_pk_mul_f32 v[26:27], v[28:29], v[26:27]
	v_lshlrev_b32_e32 v28, 16, v82
	v_cvt_pk_bf16_f32 v17, v26, v27
	v_lshlrev_b32_e32 v26, 16, v18
	v_and_b32_e32 v27, 0xffff0000, v18
	v_and_b32_e32 v29, 0xffff0000, v82
	v_pk_mul_f32 v[26:27], v[28:29], v[26:27]
	v_lshlrev_b32_e32 v28, 16, v83
	v_cvt_pk_bf16_f32 v18, v26, v27
	v_lshlrev_b32_e32 v26, 16, v19
	v_and_b32_e32 v27, 0xffff0000, v19
	v_and_b32_e32 v29, 0xffff0000, v83
	v_pk_mul_f32 v[26:27], v[28:29], v[26:27]
	s_nop 0
	v_cvt_pk_bf16_f32 v19, v26, v27
	global_store_dwordx4 v[24:25], v[16:19], off sc1
	s_waitcnt lgkmcnt(0)
	s_nop 0
	v_lshlrev_b32_e32 v16, 16, v20
	v_and_b32_e32 v17, 0xffff0000, v20
	s_waitcnt vmcnt(7)
	v_lshlrev_b32_e32 v18, 16, v10
	v_and_b32_e32 v19, 0xffff0000, v10
	v_pk_mul_f32 v[16:17], v[18:19], v[16:17]
	v_lshlrev_b32_e32 v18, 16, v11
	v_cvt_pk_bf16_f32 v10, v16, v17
	v_lshlrev_b32_e32 v16, 16, v21
	v_and_b32_e32 v17, 0xffff0000, v21
	v_and_b32_e32 v19, 0xffff0000, v11
	v_pk_mul_f32 v[16:17], v[18:19], v[16:17]
	v_lshlrev_b32_e32 v18, 16, v12
	v_cvt_pk_bf16_f32 v11, v16, v17
	v_lshlrev_b32_e32 v16, 16, v22
	v_and_b32_e32 v17, 0xffff0000, v22
	v_and_b32_e32 v19, 0xffff0000, v12
	v_pk_mul_f32 v[16:17], v[18:19], v[16:17]
	v_lshlrev_b32_e32 v18, 16, v13
	v_cvt_pk_bf16_f32 v12, v16, v17
	v_lshlrev_b32_e32 v16, 16, v23
	v_and_b32_e32 v17, 0xffff0000, v23
	v_and_b32_e32 v19, 0xffff0000, v13
	v_pk_mul_f32 v[16:17], v[18:19], v[16:17]
	v_add_co_u32_e32 v20, vcc, s68, v24
	v_cvt_pk_bf16_f32 v13, v16, v17
	ds_read_b128 v[16:19], v0 offset:53248
	v_addc_co_u32_e32 v21, vcc, 0, v25, vcc
	global_store_dwordx4 v[20:21], v[10:13], off sc1
	ds_read_b128 v[10:13], v0 offset:54272
	s_waitcnt lgkmcnt(1)
	v_lshlrev_b32_e32 v20, 16, v16
	v_and_b32_e32 v21, 0xffff0000, v16
	s_waitcnt vmcnt(7)
	v_lshlrev_b32_e32 v22, 16, v6
	v_and_b32_e32 v23, 0xffff0000, v6
	v_pk_mul_f32 v[20:21], v[22:23], v[20:21]
	v_lshlrev_b32_e32 v16, 16, v17
	v_cvt_pk_bf16_f32 v6, v20, v21
	v_and_b32_e32 v17, 0xffff0000, v17
	v_lshlrev_b32_e32 v20, 16, v7
	v_and_b32_e32 v21, 0xffff0000, v7
	v_pk_mul_f32 v[16:17], v[20:21], v[16:17]
	v_lshlrev_b32_e32 v20, 16, v8
	v_cvt_pk_bf16_f32 v7, v16, v17
	v_lshlrev_b32_e32 v16, 16, v18
	v_and_b32_e32 v17, 0xffff0000, v18
	v_and_b32_e32 v21, 0xffff0000, v8
	v_pk_mul_f32 v[16:17], v[20:21], v[16:17]
	v_lshlrev_b32_e32 v18, 16, v9
	v_cvt_pk_bf16_f32 v8, v16, v17
	v_lshlrev_b32_e32 v16, 16, v19
	v_and_b32_e32 v17, 0xffff0000, v19
	v_and_b32_e32 v19, 0xffff0000, v9
	v_pk_mul_f32 v[16:17], v[18:19], v[16:17]
	s_nop 0
	v_cvt_pk_bf16_f32 v9, v16, v17
	v_add_co_u32_e32 v16, vcc, s70, v24
	s_nop 1
	v_addc_co_u32_e32 v17, vcc, 0, v25, vcc
	global_store_dwordx4 v[16:17], v[6:9], off sc1
	s_waitcnt lgkmcnt(0)
	s_nop 0
	v_lshlrev_b32_e32 v6, 16, v10
	v_and_b32_e32 v7, 0xffff0000, v10
	s_waitcnt vmcnt(7)
	v_lshlrev_b32_e32 v8, 16, v2
	v_and_b32_e32 v9, 0xffff0000, v2
	v_pk_mul_f32 v[6:7], v[8:9], v[6:7]
	v_lshlrev_b32_e32 v8, 16, v3
	v_cvt_pk_bf16_f32 v2, v6, v7
	v_lshlrev_b32_e32 v6, 16, v11
	v_and_b32_e32 v7, 0xffff0000, v11
	v_and_b32_e32 v9, 0xffff0000, v3
	v_pk_mul_f32 v[6:7], v[8:9], v[6:7]
	v_lshlrev_b32_e32 v8, 16, v4
	v_cvt_pk_bf16_f32 v3, v6, v7
	v_lshlrev_b32_e32 v6, 16, v12
	v_and_b32_e32 v7, 0xffff0000, v12
	v_and_b32_e32 v9, 0xffff0000, v4
	v_pk_mul_f32 v[6:7], v[8:9], v[6:7]
	v_lshlrev_b32_e32 v8, 16, v5
	v_cvt_pk_bf16_f32 v4, v6, v7
	v_lshlrev_b32_e32 v6, 16, v13
	v_and_b32_e32 v7, 0xffff0000, v13
	v_and_b32_e32 v9, 0xffff0000, v5
	v_pk_mul_f32 v[6:7], v[8:9], v[6:7]
	s_nop 0
	v_cvt_pk_bf16_f32 v5, v6, v7
	v_add_co_u32_e32 v6, vcc, 0xc000, v24
	s_nop 1
	v_addc_co_u32_e32 v7, vcc, 0, v25, vcc
	s_and_b64 vcc, exec, s[0:1]
	global_store_dwordx4 v[6:7], v[2:5], off sc1
	s_cbranch_vccnz .LBB0_544
	s_xor_b32 s20, s77, 1
	s_cmpk_gt_i32 s14, 0x3ff
	s_mov_b64 s[0:1], -1
	s_cbranch_scc1 .LBB0_661
	v_add_f32_e32 v0, v87, v15
	v_add_f32_e32 v2, v0, v92
	v_add_f32_e32 v6, v2, v91
	v_lshlrev_b32_e32 v5, 2, v206
	v_mov_b32_e32 v3, v6
	s_nop 1
	v_add_f32_dpp v3, v3, v3 row_shr:1 row_mask:0xf bank_mask:0xf
	s_nop 1
	v_add_f32_dpp v3, v3, v3 row_shr:2 row_mask:0xf bank_mask:0xf
	s_nop 1
	v_add_f32_dpp v3, v3, v3 row_shr:4 row_mask:0xf bank_mask:0xf
	s_nop 1
	v_add_f32_dpp v3, v3, v3 row_shr:8 row_mask:0xf bank_mask:0xf
	s_nop 1
	v_add_f32_dpp v3, v3, v3 row_bcast:15 row_mask:0xa bank_mask:0xf
	s_nop 1
	v_add_f32_dpp v3, v3, v3 row_bcast:31 row_mask:0xc bank_mask:0xf
	s_nop 0
	v_sub_f32_e32 v8, v3, v6
	v_xad_u32 v4, v5, -1, s15
	v_add_f32_e32 v5, v87, v8
	v_add_f32_e32 v3, v0, v8
	v_add_f32_e32 v0, v6, v8
	v_sub_f32_e32 v6, v5, v87
	v_cmp_ge_f32_e64 s[0:1], v6, -v197
	v_sub_f32_e32 v6, v3, v15
	v_add_f32_e32 v2, v2, v8
	v_cmp_lt_i32_e64 s[10:11], 0, v4
	v_cmp_ge_f32_e64 s[16:17], v6, -v197
	v_cmp_lt_i32_e64 s[12:13], -1, v4
	s_and_b64 s[16:17], s[10:11], s[16:17]
	s_bcnt1_i32_b64 s60, s[16:17]
	v_sub_f32_e32 v8, v2, v92
	s_and_b64 vcc, s[12:13], s[0:1]
	s_bcnt1_i32_b64 s61, vcc
	s_add_i32 s60, s60, s61
	v_cmp_lt_i32_e64 s[0:1], 1, v4
	v_cmp_ge_f32_e64 s[16:17], v8, -v197
	s_and_b64 s[16:17], s[0:1], s[16:17]
	s_bcnt1_i32_b64 s61, s[16:17]
	s_add_i32 s60, s60, s61
	v_sub_f32_e32 v9, v0, v91
	v_cmp_lt_i32_e32 vcc, 2, v4
	v_cmp_ge_f32_e64 s[16:17], v9, -v197
	s_and_b64 s[16:17], vcc, s[16:17]
	s_bcnt1_i32_b64 s61, s[16:17]
	s_add_i32 s60, s60, s61
	s_lshl_b32 s16, s20, 10
	s_add_i32 s56, s16, 0
	s_add_i32 s56, s56, 0x24800
	s_and_saveexec_b64 s[16:17], s[12:13]
	s_cbranch_execnz .LBB0_664
	s_or_b64 exec, exec, s[16:17]
	v_lshlrev_b32_e32 v4, 2, v4
	s_and_saveexec_b64 s[12:13], s[10:11]
	s_cbranch_execnz .LBB0_665
